# grid seams: arrival inside the XCC through the flags, class leader does the write-back and the cross-XCC arrive (no per-XCC atomic counter in flag mode)
# baseline (speedup 1.0000x reference)
.Lxb_have:
	v_readfirstlane_b32 s10, v0
	v_readfirstlane_b32 s11, v1
	v_readlane_b32 s8, v240, 60
	v_mov_b32_e32 v2, 1
	s_nop 1
	v_mov_b32_e32 v4, s8
	ds_read_b32 v4, v4 offset:8
	v_readlane_b32 s8, v240, 0
	s_nop 0
	s_lshl_b32 s9, s8, 6
	s_add_u32 s9, s9, 0x4000
	s_add_u32 s14, s6, s9
	s_addc_u32 s15, s7, 0
	s_waitcnt lgkmcnt(0)
	v_readfirstlane_b32 s9, v4
	s_mov_b32 s98, s9
	s_cmp_eq_u32 s9, 1
	s_cbranch_scc0 .Lxb_grid
	s_mov_b32 s9, 0x3cfdf3f4
	s_bitcmp1_b32 s9, s70
	s_cbranch_scc0 .Lxb_grid
	s_and_b32 s9, s8, 7
	s_lshl_b32 s9, s9, 8
	s_add_u32 s9, s9, 0x12000
	s_add_u32 s12, s6, s9
	s_addc_u32 s13, s7, 0
	s_lshr_b32 s9, s8, 3
	s_lshl_b32 s9, s9, 2
	s_bfe_u32 s9, s8, 0x20003
	s_lshl_b32 s9, s9, 2
	s_mov_b32 exec_lo, 0xff
	s_mov_b32 exec_hi, 0
	v_mbcnt_lo_u32_b32 v3, -1, 0
	v_lshlrev_b32_e32 v3, 4, v3
	v_add_u32_e32 v3, s9, v3
	s_mov_b32 s9, 0

.Lxb_grid:
	s_add_i32 s100, s100, 1
	s_mul_i32 s11, s11, s100
	s_mov_b32 s9, 0
	s_cmp_eq_u32 s98, 1
	s_cbranch_scc0 .Lxb_grid_ctr
	s_cmp_gt_u32 s8, 7
	s_cbranch_scc1 .Lxb_poll
	s_lshl_b32 s12, s8, 8
	s_add_u32 s12, s12, 0x12000
	s_add_u32 s12, s6, s12
	s_addc_u32 s13, s7, 0
	s_mov_b32 exec_lo, -1
	s_mov_b32 exec_hi, 0
	v_mbcnt_lo_u32_b32 v3, -1, 0
	v_lshlrev_b32_e32 v3, 2, v3

.Lxb_gldone:
	s_mov_b64 exec, 1
	s_mov_b32 s9, 0
	s_branch .Lxb_xlast
.Lxb_grid_ctr:
	s_mul_i32 s10, s10, s100
	s_add_u32 s12, s6, s3
	s_addc_u32 s13, s7, 0
	global_atomic_add v3, v196, v2, s[12:13] offset:1024 sc0
	s_waitcnt vmcnt(0)
	v_add_u32_e32 v3, 1, v3
	v_cmp_eq_u32_e32 vcc, s10, v3
	s_cbranch_vccz .Lxb_poll
.Lxb_xlast:
	buffer_wbl2 sc1
	v_readlane_b32 s12, v240, 46
	v_readlane_b32 s13, v240, 47
	s_waitcnt vmcnt(0)
	s_nop 3
	global_atomic_add v3, v165, v2, s[12:13] sc0
	s_waitcnt vmcnt(0)
	v_add_u32_e32 v3, 1, v3
	v_cmp_eq_u32_e32 vcc, s11, v3
	s_cbranch_vccz .Lxb_poll
	s_add_u32 s12, s6, 0x4000
	s_addc_u32 s13, s7, 0
	s_mov_b64 exec, -1
	v_mbcnt_lo_u32_b32 v3, -1, 0
	v_mbcnt_hi_u32_b32 v3, -1, v3
	v_mov_b32_e32 v2, 1
	v_lshlrev_b32_e32 v3, 6, v3
	v_add_u32_e32 v4, 0x1000, v3
	v_add_u32_e32 v5, 0x2000, v3
	v_add_u32_e32 v6, 0x3000, v3
	global_atomic_add v3, v2, s[12:13]
	global_atomic_add v4, v2, s[12:13]
	global_atomic_add v5, v2, s[12:13]
	global_atomic_add v6, v2, s[12:13]
	s_waitcnt vmcnt(4)
	s_mov_b64 exec, 1
	s_branch .LBB0_463
